# prompt loop software-pipelined across the tile boundary (staging writes early in the tile between two barriers, next tile's first LDS reads issued in the tail) on top of the three-site decode loop
# baseline (speedup 1.0000x reference)
.LBB0_819:
	v_max3_f32 v2, v4, v20, v5
	v_max3_f32 v49, v21, v6, v22
	s_ashr_i32 s21, s4, 1
	v_max3_f32 v2, v2, v7, v23
	v_max3_f32 v49, v49, v8, v24
	s_lshl_b32 s23, s35, 2
	v_max3_f32 v2, v2, v9, v25
	v_max3_f32 v49, v49, v10, v26
	v_and_b32_e32 v88, 16, v48
	v_max3_f32 v2, v2, v11, v27
	v_max3_f32 v49, v49, v12, v28
	s_mov_b32 s4, 1
	v_max3_f32 v2, v2, v13, v29
	v_max3_f32 v49, v49, v14, v30
	s_nop 0
	v_max3_f32 v2, v2, v15, v31
	v_max3_f32 v49, v49, v16, v32
	s_nop 0
	v_max3_f32 v2, v2, v17, v33
	v_max3_f32 v49, v49, v18, v34
	s_nop 0
	v_max3_f32 v2, v2, v49, v19
	s_nop 0
	v_max_f32_e32 v49, v35, v35
	v_max_f32_e32 v2, v2, v2
	v_max_f32_e32 v2, v2, v49
	v_mov_b32_e32 v49, v2
	s_nop 1
	v_permlane32_swap_b32_e32 v2, v49
	v_max_f32_e32 v49, v49, v49
	v_max_f32_e32 v2, v2, v2
	v_max_f32_e32 v2, v2, v49
	v_mul_f32_e32 v2, 0x3f800000, v2
	v_cmp_neq_f32_e32 vcc, s78, v2
	s_cmp_eq_u64 vcc, 0
	v_max_f32_e32 v49, 0xff800000, v2
	s_cselect_b64 vcc, -1, 0
	v_cndmask_b32_e32 v159, v49, v230, vcc
	v_fma_f32 v2, v4, 1.0, -v159
	v_exp_f32_e32 v84, v2
	v_fma_f32 v2, v20, 1.0, -v159
	v_exp_f32_e32 v85, v2
	v_fma_f32 v2, v5, 1.0, -v159
	v_fma_f32 v4, v21, 1.0, -v159
	v_exp_f32_e32 v2, v2
	v_exp_f32_e32 v20, v4
	v_add_f32_e32 v21, v85, v84
	v_cvt_pk_bf16_f32 v144, v84, v2
	v_pk_add_f32 v[4:5], v[20:21], v[2:3]
	v_cvt_pk_bf16_f32 v136, v85, v20
	v_pk_add_f32 v[50:51], v[4:5], v[4:5] op_sel_hi:[0,1]
	v_fma_f32 v4, v6, 1.0, -v159
	v_exp_f32_e32 v21, v4
	v_fma_f32 v4, v22, 1.0, -v159
	v_exp_f32_e32 v86, v4
	v_fma_f32 v4, v7, 1.0, -v159
	v_exp_f32_e32 v50, v4
	v_fma_f32 v4, v23, 1.0, -v159
	v_exp_f32_e32 v6, v4
	v_add_f32_e32 v7, v86, v21
	v_cvt_pk_bf16_f32 v145, v21, v50
	v_pk_add_f32 v[4:5], v[6:7], v[50:51]
	s_nop 0
	v_pk_add_f32 v[22:23], v[4:5], v[4:5] op_sel_hi:[0,1]
	v_fma_f32 v4, v8, 1.0, -v159
	v_exp_f32_e32 v7, v4
	v_fma_f32 v4, v24, 1.0, -v159
	v_exp_f32_e32 v51, v4
	v_fma_f32 v4, v9, 1.0, -v159
	v_exp_f32_e32 v22, v4
	v_fma_f32 v4, v25, 1.0, -v159
	v_exp_f32_e32 v8, v4
	v_add_f32_e32 v9, v51, v7
	v_cvt_pk_bf16_f32 v146, v7, v22
	v_cvt_pk_bf16_f32 v137, v86, v6
	v_pk_add_f32 v[4:5], v[8:9], v[22:23]
	v_cvt_pk_bf16_f32 v138, v51, v8
	v_pk_add_f32 v[24:25], v[4:5], v[4:5] op_sel_hi:[0,1]
	v_fma_f32 v4, v10, 1.0, -v159
	v_exp_f32_e32 v9, v4
	v_fma_f32 v4, v26, 1.0, -v159
	v_exp_f32_e32 v23, v4
	v_fma_f32 v4, v11, 1.0, -v159
	v_exp_f32_e32 v24, v4
	v_fma_f32 v4, v27, 1.0, -v159
	v_exp_f32_e32 v10, v4
	v_lshrrev_b32_e32 v4, 2, v48
	v_add_f32_e32 v11, v23, v9
	v_and_or_b32 v87, v4, 3, v154
	v_pk_add_f32 v[4:5], v[10:11], v[24:25]
	v_lshlrev_b32_e32 v48, 2, v48
	v_pk_add_f32 v[26:27], v[4:5], v[4:5] op_sel_hi:[0,1]
	v_fma_f32 v4, v12, 1.0, -v159
	v_exp_f32_e32 v11, v4
	v_fma_f32 v4, v28, 1.0, -v159
	v_exp_f32_e32 v25, v4
	v_fma_f32 v4, v13, 1.0, -v159
	v_exp_f32_e32 v26, v4
	v_fma_f32 v4, v29, 1.0, -v159
	v_exp_f32_e32 v12, v4
	v_add_f32_e32 v13, v25, v11
	v_mul_u32_u24_e32 v87, 0xc0, v87
	v_cvt_pk_bf16_f32 v147, v9, v24
	v_pk_add_f32 v[4:5], v[12:13], v[26:27]
	v_cvt_pk_bf16_f32 v140, v11, v26
	v_pk_add_f32 v[28:29], v[4:5], v[4:5] op_sel_hi:[0,1]
	v_fma_f32 v4, v14, 1.0, -v159
	v_exp_f32_e32 v13, v4
	v_fma_f32 v4, v30, 1.0, -v159
	v_exp_f32_e32 v27, v4
	v_fma_f32 v4, v15, 1.0, -v159
	v_exp_f32_e32 v28, v4
	v_fma_f32 v4, v31, 1.0, -v159
	v_exp_f32_e32 v14, v4
	v_add_f32_e32 v15, v27, v13
	v_cvt_pk_bf16_f32 v141, v13, v28
	v_cvt_pk_bf16_f32 v139, v23, v10
	v_pk_add_f32 v[4:5], v[14:15], v[28:29]
	v_cvt_pk_bf16_f32 v132, v25, v12
	v_pk_add_f32 v[30:31], v[4:5], v[4:5] op_sel_hi:[0,1]
	v_fma_f32 v4, v16, 1.0, -v159
	v_exp_f32_e32 v15, v4
	v_fma_f32 v4, v32, 1.0, -v159
	v_exp_f32_e32 v29, v4
	v_fma_f32 v4, v17, 1.0, -v159
	v_exp_f32_e32 v30, v4
	v_fma_f32 v4, v33, 1.0, -v159
	v_exp_f32_e32 v16, v4
	v_and_or_b32 v4, v48, 12, v88
	v_add_f32_e32 v17, v29, v15
	v_lshl_or_b32 v162, v4, 1, v87
	v_pk_add_f32 v[4:5], v[16:17], v[30:31]
	v_cvt_pk_bf16_f32 v142, v15, v30
	v_pk_add_f32 v[32:33], v[4:5], v[4:5] op_sel_hi:[0,1]
	v_fma_f32 v4, v18, 1.0, -v159
	v_exp_f32_e32 v17, v4
	v_fma_f32 v4, v34, 1.0, -v159
	v_exp_f32_e32 v31, v4
	v_fma_f32 v4, v19, 1.0, -v159
	v_exp_f32_e32 v32, v4
	v_fma_f32 v4, v35, 1.0, -v159
	v_exp_f32_e32 v18, v4
	v_sub_f32_e32 v4, 0xff800000, v49
	v_exp_f32_e32 v34, v4
	v_add_f32_e32 v19, v31, v17
	v_pk_add_f32 v[4:5], v[18:19], v[32:33]
	v_cvt_pk_bf16_f32 v143, v17, v32
	v_add_f32_e32 v5, v4, v5
	v_mul_f32_e32 v4, 0, v34
	v_cndmask_b32_e64 v4, v4, 0, vcc
	v_add_f32_e32 v152, v4, v5
	v_cvt_pk_bf16_f32 v133, v27, v14
	v_cvt_pk_bf16_f32 v134, v29, v16
	v_cvt_pk_bf16_f32 v135, v31, v18
	v_mad_u64_u32 v[20:21], s[50:51], v45, s80, v[44:45]
	v_mov_b32_e32 v5, v4
	v_mov_b32_e32 v6, v4
	v_mov_b32_e32 v7, v4
	v_mov_b32_e32 v8, v4
	v_mov_b32_e32 v9, v4
	v_mov_b32_e32 v10, v4
	v_mov_b32_e32 v11, v4
	v_mov_b32_e32 v12, v4
	v_mov_b32_e32 v13, v4
	v_mov_b32_e32 v14, v4
	v_mov_b32_e32 v15, v4
	v_mov_b32_e32 v16, v4
	v_mov_b32_e32 v17, v4
	v_mov_b32_e32 v18, v4
	v_mov_b32_e32 v19, v4
	v_add_u32_e32 v151, 0, v20
	s_andn2_b64 vcc, exec, s[2:3]
	s_waitcnt vmcnt(1)
	ds_write_b128 v157, v[40:43]
	ds_write_b64 v158, v[46:47] offset:128
	s_waitcnt vmcnt(0)
	ds_write_b128 v151, v[36:39] offset:26624
	s_waitcnt lgkmcnt(0)
	s_barrier
	s_cbranch_vccnz .LBB0_859
	v_mov_b64_e32 v[34:35], v[18:19]
	v_mov_b64_e32 v[98:99], v[66:67]
	v_mov_b64_e32 v[36:37], v[68:69]
	s_add_i32 s50, s23, -1
	s_mov_b32 s51, 1
	s_mov_b32 s52, s68
	s_mov_b32 s53, s67
	v_mov_b64_e32 v[32:33], v[16:17]
	v_mov_b64_e32 v[30:31], v[14:15]
	v_mov_b64_e32 v[28:29], v[12:13]
	v_mov_b64_e32 v[26:27], v[10:11]
	v_mov_b64_e32 v[24:25], v[8:9]
	v_mov_b64_e32 v[22:23], v[6:7]
	v_mov_b64_e32 v[20:21], v[4:5]
	v_mov_b64_e32 v[96:97], v[64:65]
	v_mov_b64_e32 v[94:95], v[62:63]
	v_mov_b64_e32 v[92:93], v[60:61]
	v_mov_b64_e32 v[90:91], v[58:59]
	v_mov_b64_e32 v[88:89], v[56:57]
	v_mov_b64_e32 v[86:87], v[54:55]
	v_mov_b64_e32 v[84:85], v[52:53]
	v_mov_b64_e32 v[38:39], v[70:71]
	v_mov_b64_e32 v[40:41], v[72:73]
	v_mov_b64_e32 v[42:43], v[74:75]
	v_mov_b64_e32 v[44:45], v[76:77]
	v_mov_b64_e32 v[46:47], v[78:79]
	v_mov_b64_e32 v[48:49], v[80:81]
	v_mov_b64_e32 v[50:51], v[82:83]
	v_xor_b32_e32 v234, 0x80000000, v159
	v_xor_b32_e32 v235, 0x80000000, v159
	v_xor_b32_e32 v236, 0x80000000, v159
	v_xor_b32_e32 v237, 0x80000000, v159
	v_xor_b32_e32 v238, 0x80000000, v159
	v_xor_b32_e32 v239, 0x80000000, v159
	v_xor_b32_e32 v240, 0x80000000, v159
	v_xor_b32_e32 v241, 0x80000000, v159
	v_xor_b32_e32 v242, 0x80000000, v159
	v_xor_b32_e32 v243, 0x80000000, v159
	v_xor_b32_e32 v244, 0x80000000, v159
	v_xor_b32_e32 v245, 0x80000000, v159
	v_xor_b32_e32 v246, 0x80000000, v159
	v_xor_b32_e32 v247, 0x80000000, v159
	v_xor_b32_e32 v248, 0x80000000, v159
	v_xor_b32_e32 v249, 0x80000000, v159
	v_sub_f32_e32 v84, v84, v159
	v_sub_f32_e32 v36, v36, v159
	v_sub_f32_e32 v85, v85, v159
	v_sub_f32_e32 v37, v37, v159
	v_sub_f32_e32 v86, v86, v159
	v_sub_f32_e32 v38, v38, v159
	v_sub_f32_e32 v87, v87, v159
	v_sub_f32_e32 v39, v39, v159
	v_sub_f32_e32 v88, v88, v159
	v_sub_f32_e32 v40, v40, v159
	v_sub_f32_e32 v89, v89, v159
	v_sub_f32_e32 v41, v41, v159
	v_sub_f32_e32 v90, v90, v159
	v_sub_f32_e32 v42, v42, v159
	v_sub_f32_e32 v91, v91, v159
	v_sub_f32_e32 v43, v43, v159
	v_sub_f32_e32 v92, v92, v159
	v_sub_f32_e32 v44, v44, v159
	v_sub_f32_e32 v93, v93, v159
	v_sub_f32_e32 v45, v45, v159
	v_sub_f32_e32 v94, v94, v159
	v_sub_f32_e32 v46, v46, v159
	v_sub_f32_e32 v95, v95, v159
	v_sub_f32_e32 v47, v47, v159
	v_sub_f32_e32 v96, v96, v159
	v_sub_f32_e32 v48, v48, v159
	v_sub_f32_e32 v97, v97, v159
	v_sub_f32_e32 v49, v49, v159
	v_sub_f32_e32 v98, v98, v159
	v_sub_f32_e32 v50, v50, v159
	v_sub_f32_e32 v99, v99, v159
	v_sub_f32_e32 v51, v51, v159
	v_add_u32_e32 v163, 0, v162
	s_add_i32 s2, s52, 0xfffff000
	buffer_load_dwordx2 v[108:109], v161, s[12:15], s2 offen
	s_add_i32 s3, s53, 0xfe020000
	buffer_load_dwordx4 v[104:107], v150, s[12:15], s3 offen
	s_add_i32 s4, s53, 0xfffe0000
	buffer_load_dwordx4 v[100:103], v150, s[12:15], s4 offen
	ds_read_b128 v[200:203], v156 offset:51200
	ds_read_b128 v[204:207], v156 offset:51232
	ds_read_b128 v[208:211], v156 offset:51264
	ds_read_b128 v[212:215], v156 offset:51296
	ds_read_b128 v[216:219], v156 offset:51328
	ds_read_b128 v[250:253], v156 offset:51360
	s_waitcnt lgkmcnt(0)
	ds_read_b64_tr_b16 v[164:165], v162 offset:26624
	ds_read_b64_tr_b16 v[166:167], v162 offset:28160
	ds_read_b64_tr_b16 v[168:169], v162 offset:26688
	ds_read_b64_tr_b16 v[170:171], v162 offset:28224
	ds_read_b64_tr_b16 v[172:173], v162 offset:29696
	ds_read_b64_tr_b16 v[174:175], v162 offset:31232
.LBB0_822:
	s_mov_b32 s5, 0
	v_exp_f32_e32 v124, v84
	v_exp_f32_e32 v125, v85
	v_exp_f32_e32 v126, v86
	v_add_f32_e32 v224, v124, v125
	s_waitcnt lgkmcnt(4)
	v_mfma_f32_32x32x16_bf16 v[4:19], v[164:167], v[144:147], v[4:19]
	v_exp_f32_e32 v127, v87
	v_cvt_pk_bf16_f32 v184, v124, v125
	v_mov_b32_e32 v254, v224
	v_exp_f32_e32 v128, v88
	s_waitcnt lgkmcnt(2)
	v_mfma_f32_32x32x16_bf16 v[20:35], v[168:171], v[144:147], v[20:35]
	s_barrier
	s_waitcnt vmcnt(0)
	ds_write_b128 v157, v[104:107] offset:13312
	ds_write_b64 v158, v[108:109] offset:13440
	ds_write_b128 v151, v[100:103] offset:38912
	buffer_load_dwordx2 v[108:109], v161, s[12:15], s52 offen
	s_add_i32 s3, s53, 0xfe040000
	buffer_load_dwordx4 v[104:107], v150, s[12:15], s3 offen
	buffer_load_dwordx4 v[100:103], v150, s[12:15], s53 offen
	ds_read_b64_tr_b16 v[176:177], v162 offset:29760
	ds_read_b64_tr_b16 v[178:179], v162 offset:31296
	v_add_f32_e32 v226, v126, v127
	v_exp_f32_e32 v129, v89
	v_cvt_pk_bf16_f32 v185, v126, v127
	v_add_f32_e32 v254, v254, v226
	s_waitcnt lgkmcnt(5)
	v_mfma_f32_32x32x16_bf16 v[4:19], v[172:175], v[140:143], v[4:19]
	ds_read_b64_tr_b16 v[164:165], v162 offset:32768
	ds_read_b64_tr_b16 v[166:167], v162 offset:34304
	v_exp_f32_e32 v130, v90
	v_add_f32_e32 v233, v128, v129
	v_exp_f32_e32 v131, v91
	v_cvt_pk_bf16_f32 v186, v128, v129
	s_waitcnt lgkmcnt(2)
	v_mfma_f32_32x32x16_bf16 v[20:35], v[176:179], v[140:143], v[20:35]
	s_barrier
	ds_read_b64_tr_b16 v[168:169], v162 offset:32832
	ds_read_b64_tr_b16 v[170:171], v162 offset:34368
	v_add_f32_e32 v254, v254, v233
	v_exp_f32_e32 v124, v92
	v_add_f32_e32 v224, v130, v131
	v_exp_f32_e32 v125, v93
	s_waitcnt lgkmcnt(2)
	v_mfma_f32_32x32x16_bf16 v[4:19], v[164:167], v[136:139], v[4:19]
	ds_read_b64_tr_b16 v[172:173], v162 offset:35840
	ds_read_b64_tr_b16 v[174:175], v162 offset:37376
	v_cvt_pk_bf16_f32 v187, v130, v131
	v_add_f32_e32 v254, v254, v224
	v_exp_f32_e32 v126, v94
	v_add_f32_e32 v226, v124, v125
	s_waitcnt lgkmcnt(2)
	v_mfma_f32_32x32x16_bf16 v[20:35], v[168:171], v[136:139], v[20:35]
	ds_read_b64_tr_b16 v[176:177], v162 offset:35904
	ds_read_b64_tr_b16 v[178:179], v162 offset:37440
	v_exp_f32_e32 v127, v95
	v_cvt_pk_bf16_f32 v188, v124, v125
	v_add_f32_e32 v254, v254, v226
	v_exp_f32_e32 v128, v96
	s_waitcnt lgkmcnt(2)
	v_mfma_f32_32x32x16_bf16 v[4:19], v[172:175], v[132:135], v[4:19]
	ds_read_b128 v[180:183], v155 offset:0
	ds_read_b128 v[112:115], v155 offset:6656
	v_add_f32_e32 v233, v126, v127
	v_exp_f32_e32 v129, v97
	v_cvt_pk_bf16_f32 v189, v126, v127
	v_add_f32_e32 v254, v254, v233
	s_waitcnt lgkmcnt(2)
	v_mfma_f32_32x32x16_bf16 v[20:35], v[176:179], v[132:135], v[20:35]
	ds_read_b128 v[116:119], v155 offset:32
	ds_read_b128 v[120:123], v155 offset:6688
	v_exp_f32_e32 v130, v98
	v_add_f32_e32 v224, v128, v129
	v_exp_f32_e32 v131, v99
	v_cvt_pk_bf16_f32 v190, v128, v129
	s_waitcnt lgkmcnt(3)
	v_mfma_f32_32x32x16_bf16 v[52:67], v[180:183], v[200:203], v[234:249]
	ds_read_b128 v[180:183], v155 offset:64
	v_add_f32_e32 v254, v254, v224
	v_exp_f32_e32 v124, v36
	v_add_f32_e32 v226, v130, v131
	v_exp_f32_e32 v125, v37
	s_waitcnt lgkmcnt(3)
	v_mfma_f32_32x32x16_bf16 v[68:83], v[112:115], v[200:203], v[234:249]
	ds_read_b128 v[112:115], v155 offset:6720
	v_cvt_pk_bf16_f32 v191, v130, v131
	v_add_f32_e32 v254, v254, v226
	v_exp_f32_e32 v126, v38
	v_add_f32_e32 v233, v124, v125
	s_waitcnt lgkmcnt(3)
	v_mfma_f32_32x32x16_bf16 v[52:67], v[116:119], v[204:207], v[52:67]
	ds_read_b128 v[116:119], v155 offset:96
	v_exp_f32_e32 v127, v39
	v_cvt_pk_bf16_f32 v192, v124, v125
	v_add_f32_e32 v254, v254, v233
	v_exp_f32_e32 v128, v40
	s_waitcnt lgkmcnt(3)
	v_mfma_f32_32x32x16_bf16 v[68:83], v[120:123], v[204:207], v[68:83]
	ds_read_b128 v[120:123], v155 offset:6752
	v_add_f32_e32 v224, v126, v127
	v_exp_f32_e32 v129, v41
	v_cvt_pk_bf16_f32 v193, v126, v127
	v_add_f32_e32 v254, v254, v224
	s_waitcnt lgkmcnt(3)
	v_mfma_f32_32x32x16_bf16 v[52:67], v[180:183], v[208:211], v[52:67]
	ds_read_b128 v[180:183], v155 offset:128
	v_exp_f32_e32 v130, v42
	v_add_f32_e32 v226, v128, v129
	v_exp_f32_e32 v131, v43
	v_cvt_pk_bf16_f32 v194, v128, v129
	s_waitcnt lgkmcnt(3)
	v_mfma_f32_32x32x16_bf16 v[68:83], v[112:115], v[208:211], v[68:83]
	ds_read_b128 v[112:115], v155 offset:6784
	v_add_f32_e32 v254, v254, v226
	v_exp_f32_e32 v124, v44
	v_add_f32_e32 v233, v130, v131
	v_exp_f32_e32 v125, v45
	s_waitcnt lgkmcnt(3)
	v_mfma_f32_32x32x16_bf16 v[52:67], v[116:119], v[212:215], v[52:67]
	ds_read_b128 v[116:119], v155 offset:160
	v_cvt_pk_bf16_f32 v195, v130, v131
	v_add_f32_e32 v254, v254, v233
	v_exp_f32_e32 v126, v46
	v_add_f32_e32 v224, v124, v125
	s_waitcnt lgkmcnt(3)
	v_mfma_f32_32x32x16_bf16 v[68:83], v[120:123], v[212:215], v[68:83]
	ds_read_b128 v[120:123], v155 offset:6816
	v_exp_f32_e32 v127, v47
	v_cvt_pk_bf16_f32 v196, v124, v125
	v_add_f32_e32 v254, v254, v224
	v_exp_f32_e32 v128, v48
	s_waitcnt lgkmcnt(3)
	v_mfma_f32_32x32x16_bf16 v[52:67], v[180:183], v[216:219], v[52:67]
	v_add_f32_e32 v226, v126, v127
	v_exp_f32_e32 v129, v49
	v_cvt_pk_bf16_f32 v197, v126, v127
	v_add_f32_e32 v254, v254, v226
	s_waitcnt lgkmcnt(2)
	v_mfma_f32_32x32x16_bf16 v[68:83], v[112:115], v[216:219], v[68:83]
	v_exp_f32_e32 v130, v50
	v_add_f32_e32 v233, v128, v129
	v_exp_f32_e32 v131, v51
	v_cvt_pk_bf16_f32 v198, v128, v129
	s_waitcnt lgkmcnt(1)
	v_mfma_f32_32x32x16_bf16 v[52:67], v[116:119], v[250:253], v[52:67]
	v_add_f32_e32 v254, v254, v233
	v_add_f32_e32 v224, v130, v131
	v_cvt_pk_bf16_f32 v199, v130, v131
	v_add_f32_e32 v254, v254, v224
	s_waitcnt lgkmcnt(0)
	v_mfma_f32_32x32x16_bf16 v[68:83], v[120:123], v[250:253], v[68:83]
	v_cmp_lt_f32_e32 vcc, 0x43800000, v254
	s_cbranch_vccnz .LpfU_s0
.LpfU_b0:
	v_add_f32_e32 v152, v152, v254
	ds_read_b64_tr_b16 v[164:165], v162 offset:38912
	ds_read_b64_tr_b16 v[166:167], v162 offset:40448
	ds_read_b64_tr_b16 v[168:169], v162 offset:38976
	ds_read_b64_tr_b16 v[170:171], v162 offset:40512
	ds_read_b64_tr_b16 v[172:173], v162 offset:41984
	ds_read_b64_tr_b16 v[174:175], v162 offset:43520
	s_cmp_eq_u32 s5, 0
	s_cbranch_scc1 .LpfU_nr0
	s_nop 11
	v_pk_mul_f32 v[4:5], v[220:221], v[4:5] op_sel_hi:[0,1]
	v_pk_mul_f32 v[6:7], v[220:221], v[6:7] op_sel_hi:[0,1]
	v_pk_mul_f32 v[8:9], v[220:221], v[8:9] op_sel_hi:[0,1]
	v_pk_mul_f32 v[10:11], v[220:221], v[10:11] op_sel_hi:[0,1]
	v_pk_mul_f32 v[12:13], v[220:221], v[12:13] op_sel_hi:[0,1]
	v_pk_mul_f32 v[14:15], v[220:221], v[14:15] op_sel_hi:[0,1]
	v_pk_mul_f32 v[16:17], v[220:221], v[16:17] op_sel_hi:[0,1]
	v_pk_mul_f32 v[18:19], v[220:221], v[18:19] op_sel_hi:[0,1]
	v_pk_mul_f32 v[20:21], v[220:221], v[20:21] op_sel_hi:[0,1]
	v_pk_mul_f32 v[22:23], v[220:221], v[22:23] op_sel_hi:[0,1]
	v_pk_mul_f32 v[24:25], v[220:221], v[24:25] op_sel_hi:[0,1]
	v_pk_mul_f32 v[26:27], v[220:221], v[26:27] op_sel_hi:[0,1]
	v_pk_mul_f32 v[28:29], v[220:221], v[28:29] op_sel_hi:[0,1]
	v_pk_mul_f32 v[30:31], v[220:221], v[30:31] op_sel_hi:[0,1]
	v_pk_mul_f32 v[32:33], v[220:221], v[32:33] op_sel_hi:[0,1]
	v_pk_mul_f32 v[34:35], v[220:221], v[34:35] op_sel_hi:[0,1]
	v_sub_f32_e32 v52, v52, v222
	v_sub_f32_e32 v68, v68, v222
	v_sub_f32_e32 v53, v53, v222
	v_sub_f32_e32 v69, v69, v222
	v_sub_f32_e32 v54, v54, v222
	v_sub_f32_e32 v70, v70, v222
	v_sub_f32_e32 v55, v55, v222
	v_sub_f32_e32 v71, v71, v222
	v_sub_f32_e32 v56, v56, v222
	v_sub_f32_e32 v72, v72, v222
	v_sub_f32_e32 v57, v57, v222
	v_sub_f32_e32 v73, v73, v222
	v_sub_f32_e32 v58, v58, v222
	v_sub_f32_e32 v74, v74, v222
	v_sub_f32_e32 v59, v59, v222
	v_sub_f32_e32 v75, v75, v222
	v_sub_f32_e32 v60, v60, v222
	v_sub_f32_e32 v76, v76, v222
	v_sub_f32_e32 v61, v61, v222
	v_sub_f32_e32 v77, v77, v222
	v_sub_f32_e32 v62, v62, v222
	v_sub_f32_e32 v78, v78, v222
	v_sub_f32_e32 v63, v63, v222
	v_sub_f32_e32 v79, v79, v222
	v_sub_f32_e32 v64, v64, v222
	v_sub_f32_e32 v80, v80, v222
	v_sub_f32_e32 v65, v65, v222
	v_sub_f32_e32 v81, v81, v222
	v_sub_f32_e32 v66, v66, v222
	v_sub_f32_e32 v82, v82, v222
	v_sub_f32_e32 v67, v67, v222
	v_sub_f32_e32 v83, v83, v222
	v_sub_f32_e32 v234, v234, v222
	v_sub_f32_e32 v235, v235, v222
	v_sub_f32_e32 v236, v236, v222
	v_sub_f32_e32 v237, v237, v222
	v_sub_f32_e32 v238, v238, v222
	v_sub_f32_e32 v239, v239, v222
	v_sub_f32_e32 v240, v240, v222
	v_sub_f32_e32 v241, v241, v222
	v_sub_f32_e32 v242, v242, v222
	v_sub_f32_e32 v243, v243, v222
	v_sub_f32_e32 v244, v244, v222
	v_sub_f32_e32 v245, v245, v222
	v_sub_f32_e32 v246, v246, v222
	v_sub_f32_e32 v247, v247, v222
	v_sub_f32_e32 v248, v248, v222
	v_sub_f32_e32 v249, v249, v222
.LpfU_nr0:
	s_mov_b32 s5, 0
	v_exp_f32_e32 v124, v52
	v_exp_f32_e32 v125, v53
	v_exp_f32_e32 v126, v54
	v_add_f32_e32 v224, v124, v125
	s_waitcnt lgkmcnt(4)
	v_mfma_f32_32x32x16_bf16 v[4:19], v[164:167], v[184:187], v[4:19]
	v_exp_f32_e32 v127, v55
	v_cvt_pk_bf16_f32 v144, v124, v125
	v_mov_b32_e32 v254, v224
	v_exp_f32_e32 v128, v56
	s_waitcnt lgkmcnt(2)
	v_mfma_f32_32x32x16_bf16 v[20:35], v[168:171], v[184:187], v[20:35]
	s_barrier
	s_waitcnt vmcnt(0)
	ds_write_b128 v157, v[104:107]
	ds_write_b64 v158, v[108:109] offset:128
	ds_write_b128 v151, v[100:103] offset:26624
	s_add_i32 s2, s51, 2
	s_cmp_lt_i32 s2, s50
	s_cbranch_scc0 .LpfU_nl
	s_add_i32 s2, s52, 0x1000
	buffer_load_dwordx2 v[108:109], v161, s[12:15], s2 offen
	s_add_i32 s3, s53, 0xfe060000
	buffer_load_dwordx4 v[104:107], v150, s[12:15], s3 offen
	s_add_i32 s4, s53, 0x20000
	buffer_load_dwordx4 v[100:103], v150, s[12:15], s4 offen
.LpfU_nl:
	ds_read_b64_tr_b16 v[176:177], v162 offset:42048
	ds_read_b64_tr_b16 v[178:179], v162 offset:43584
	v_add_f32_e32 v226, v126, v127
	v_exp_f32_e32 v129, v57
	v_cvt_pk_bf16_f32 v145, v126, v127
	v_add_f32_e32 v254, v254, v226
	s_waitcnt lgkmcnt(5)
	v_mfma_f32_32x32x16_bf16 v[4:19], v[172:175], v[188:191], v[4:19]
	ds_read_b64_tr_b16 v[164:165], v162 offset:45056
	ds_read_b64_tr_b16 v[166:167], v162 offset:46592
	v_exp_f32_e32 v130, v58
	v_add_f32_e32 v233, v128, v129
	v_exp_f32_e32 v131, v59
	v_cvt_pk_bf16_f32 v146, v128, v129
	s_waitcnt lgkmcnt(2)
	v_mfma_f32_32x32x16_bf16 v[20:35], v[176:179], v[188:191], v[20:35]
	s_barrier
	ds_read_b64_tr_b16 v[168:169], v162 offset:45120
	ds_read_b64_tr_b16 v[170:171], v162 offset:46656
	v_add_f32_e32 v254, v254, v233
	v_exp_f32_e32 v124, v60
	v_add_f32_e32 v224, v130, v131
	v_exp_f32_e32 v125, v61
	s_waitcnt lgkmcnt(2)
	v_mfma_f32_32x32x16_bf16 v[4:19], v[164:167], v[192:195], v[4:19]
	ds_read_b64_tr_b16 v[172:173], v162 offset:48128
	ds_read_b64_tr_b16 v[174:175], v162 offset:49664
	v_cvt_pk_bf16_f32 v147, v130, v131
	v_add_f32_e32 v254, v254, v224
	v_exp_f32_e32 v126, v62
	v_add_f32_e32 v226, v124, v125
	s_waitcnt lgkmcnt(2)
	v_mfma_f32_32x32x16_bf16 v[20:35], v[168:171], v[192:195], v[20:35]
	ds_read_b64_tr_b16 v[176:177], v162 offset:48192
	ds_read_b64_tr_b16 v[178:179], v162 offset:49728
	v_exp_f32_e32 v127, v63
	v_cvt_pk_bf16_f32 v140, v124, v125
	v_add_f32_e32 v254, v254, v226
	v_exp_f32_e32 v128, v64
	s_waitcnt lgkmcnt(2)
	v_mfma_f32_32x32x16_bf16 v[4:19], v[172:175], v[196:199], v[4:19]
	ds_read_b128 v[180:183], v155 offset:13312
	ds_read_b128 v[112:115], v155 offset:19968
	v_add_f32_e32 v233, v126, v127
	v_exp_f32_e32 v129, v65
	v_cvt_pk_bf16_f32 v141, v126, v127
	v_add_f32_e32 v254, v254, v233
	s_waitcnt lgkmcnt(2)
	v_mfma_f32_32x32x16_bf16 v[20:35], v[176:179], v[196:199], v[20:35]
	ds_read_b128 v[116:119], v155 offset:13344
	ds_read_b128 v[120:123], v155 offset:20000
	v_exp_f32_e32 v130, v66
	v_add_f32_e32 v224, v128, v129
	v_exp_f32_e32 v131, v67
	v_cvt_pk_bf16_f32 v142, v128, v129
	s_waitcnt lgkmcnt(3)
	v_mfma_f32_32x32x16_bf16 v[84:99], v[180:183], v[200:203], v[234:249]
	ds_read_b128 v[180:183], v155 offset:13376
	v_add_f32_e32 v254, v254, v224
	v_exp_f32_e32 v124, v68
	v_add_f32_e32 v226, v130, v131
	v_exp_f32_e32 v125, v69
	s_waitcnt lgkmcnt(3)
	v_mfma_f32_32x32x16_bf16 v[36:51], v[112:115], v[200:203], v[234:249]
	ds_read_b128 v[112:115], v155 offset:20032
	v_cvt_pk_bf16_f32 v143, v130, v131
	v_add_f32_e32 v254, v254, v226
	v_exp_f32_e32 v126, v70
	v_add_f32_e32 v233, v124, v125
	s_waitcnt lgkmcnt(3)
	v_mfma_f32_32x32x16_bf16 v[84:99], v[116:119], v[204:207], v[84:99]
	ds_read_b128 v[116:119], v155 offset:13408
	v_exp_f32_e32 v127, v71
	v_cvt_pk_bf16_f32 v136, v124, v125
	v_add_f32_e32 v254, v254, v233
	v_exp_f32_e32 v128, v72
	s_waitcnt lgkmcnt(3)
	v_mfma_f32_32x32x16_bf16 v[36:51], v[120:123], v[204:207], v[36:51]
	ds_read_b128 v[120:123], v155 offset:20064
	v_add_f32_e32 v224, v126, v127
	v_exp_f32_e32 v129, v73
	v_cvt_pk_bf16_f32 v137, v126, v127
	v_add_f32_e32 v254, v254, v224
	s_waitcnt lgkmcnt(3)
	v_mfma_f32_32x32x16_bf16 v[84:99], v[180:183], v[208:211], v[84:99]
	ds_read_b128 v[180:183], v155 offset:13440
	v_exp_f32_e32 v130, v74
	v_add_f32_e32 v226, v128, v129
	v_exp_f32_e32 v131, v75
	v_cvt_pk_bf16_f32 v138, v128, v129
	s_waitcnt lgkmcnt(3)
	v_mfma_f32_32x32x16_bf16 v[36:51], v[112:115], v[208:211], v[36:51]
	ds_read_b128 v[112:115], v155 offset:20096
	v_add_f32_e32 v254, v254, v226
	v_exp_f32_e32 v124, v76
	v_add_f32_e32 v233, v130, v131
	v_exp_f32_e32 v125, v77
	s_waitcnt lgkmcnt(3)
	v_mfma_f32_32x32x16_bf16 v[84:99], v[116:119], v[212:215], v[84:99]
	ds_read_b128 v[116:119], v155 offset:13472
	v_cvt_pk_bf16_f32 v139, v130, v131
	v_add_f32_e32 v254, v254, v233
	v_exp_f32_e32 v126, v78
	v_add_f32_e32 v224, v124, v125
	s_waitcnt lgkmcnt(3)
	v_mfma_f32_32x32x16_bf16 v[36:51], v[120:123], v[212:215], v[36:51]
	ds_read_b128 v[120:123], v155 offset:20128
	v_exp_f32_e32 v127, v79
	v_cvt_pk_bf16_f32 v132, v124, v125
	v_add_f32_e32 v254, v254, v224
	v_exp_f32_e32 v128, v80
	s_waitcnt lgkmcnt(3)
	v_mfma_f32_32x32x16_bf16 v[84:99], v[180:183], v[216:219], v[84:99]
	v_add_f32_e32 v226, v126, v127
	v_exp_f32_e32 v129, v81
	v_cvt_pk_bf16_f32 v133, v126, v127
	v_add_f32_e32 v254, v254, v226
	s_waitcnt lgkmcnt(2)
	v_mfma_f32_32x32x16_bf16 v[36:51], v[112:115], v[216:219], v[36:51]
	v_exp_f32_e32 v130, v82
	v_add_f32_e32 v233, v128, v129
	v_exp_f32_e32 v131, v83
	v_cvt_pk_bf16_f32 v134, v128, v129
	s_waitcnt lgkmcnt(1)
	v_mfma_f32_32x32x16_bf16 v[84:99], v[116:119], v[250:253], v[84:99]
	v_add_f32_e32 v254, v254, v233
	v_add_f32_e32 v224, v130, v131
	v_cvt_pk_bf16_f32 v135, v130, v131
	v_add_f32_e32 v254, v254, v224
	s_waitcnt lgkmcnt(0)
	v_mfma_f32_32x32x16_bf16 v[36:51], v[120:123], v[250:253], v[36:51]
	v_cmp_lt_f32_e32 vcc, 0x43800000, v254
	s_cbranch_vccnz .LpfU_s1
.LpfU_b1:
	v_add_f32_e32 v152, v152, v254
	ds_read_b64_tr_b16 v[164:165], v162 offset:26624
	ds_read_b64_tr_b16 v[166:167], v162 offset:28160
	ds_read_b64_tr_b16 v[168:169], v162 offset:26688
	ds_read_b64_tr_b16 v[170:171], v162 offset:28224
	ds_read_b64_tr_b16 v[172:173], v162 offset:29696
	ds_read_b64_tr_b16 v[174:175], v162 offset:31232
	s_cmp_eq_u32 s5, 0
	s_cbranch_scc1 .LpfU_nr1
	s_nop 11
	v_pk_mul_f32 v[4:5], v[220:221], v[4:5] op_sel_hi:[0,1]
	v_pk_mul_f32 v[6:7], v[220:221], v[6:7] op_sel_hi:[0,1]
	v_pk_mul_f32 v[8:9], v[220:221], v[8:9] op_sel_hi:[0,1]
	v_pk_mul_f32 v[10:11], v[220:221], v[10:11] op_sel_hi:[0,1]
	v_pk_mul_f32 v[12:13], v[220:221], v[12:13] op_sel_hi:[0,1]
	v_pk_mul_f32 v[14:15], v[220:221], v[14:15] op_sel_hi:[0,1]
	v_pk_mul_f32 v[16:17], v[220:221], v[16:17] op_sel_hi:[0,1]
	v_pk_mul_f32 v[18:19], v[220:221], v[18:19] op_sel_hi:[0,1]
	v_pk_mul_f32 v[20:21], v[220:221], v[20:21] op_sel_hi:[0,1]
	v_pk_mul_f32 v[22:23], v[220:221], v[22:23] op_sel_hi:[0,1]
	v_pk_mul_f32 v[24:25], v[220:221], v[24:25] op_sel_hi:[0,1]
	v_pk_mul_f32 v[26:27], v[220:221], v[26:27] op_sel_hi:[0,1]
	v_pk_mul_f32 v[28:29], v[220:221], v[28:29] op_sel_hi:[0,1]
	v_pk_mul_f32 v[30:31], v[220:221], v[30:31] op_sel_hi:[0,1]
	v_pk_mul_f32 v[32:33], v[220:221], v[32:33] op_sel_hi:[0,1]
	v_pk_mul_f32 v[34:35], v[220:221], v[34:35] op_sel_hi:[0,1]
	v_sub_f32_e32 v84, v84, v222
	v_sub_f32_e32 v36, v36, v222
	v_sub_f32_e32 v85, v85, v222
	v_sub_f32_e32 v37, v37, v222
	v_sub_f32_e32 v86, v86, v222
	v_sub_f32_e32 v38, v38, v222
	v_sub_f32_e32 v87, v87, v222
	v_sub_f32_e32 v39, v39, v222
	v_sub_f32_e32 v88, v88, v222
	v_sub_f32_e32 v40, v40, v222
	v_sub_f32_e32 v89, v89, v222
	v_sub_f32_e32 v41, v41, v222
	v_sub_f32_e32 v90, v90, v222
	v_sub_f32_e32 v42, v42, v222
	v_sub_f32_e32 v91, v91, v222
	v_sub_f32_e32 v43, v43, v222
	v_sub_f32_e32 v92, v92, v222
	v_sub_f32_e32 v44, v44, v222
	v_sub_f32_e32 v93, v93, v222
	v_sub_f32_e32 v45, v45, v222
	v_sub_f32_e32 v94, v94, v222
	v_sub_f32_e32 v46, v46, v222
	v_sub_f32_e32 v95, v95, v222
	v_sub_f32_e32 v47, v47, v222
	v_sub_f32_e32 v96, v96, v222
	v_sub_f32_e32 v48, v48, v222
	v_sub_f32_e32 v97, v97, v222
	v_sub_f32_e32 v49, v49, v222
	v_sub_f32_e32 v98, v98, v222
	v_sub_f32_e32 v50, v50, v222
	v_sub_f32_e32 v99, v99, v222
	v_sub_f32_e32 v51, v51, v222
	v_sub_f32_e32 v234, v234, v222
	v_sub_f32_e32 v235, v235, v222
	v_sub_f32_e32 v236, v236, v222
	v_sub_f32_e32 v237, v237, v222
	v_sub_f32_e32 v238, v238, v222
	v_sub_f32_e32 v239, v239, v222
	v_sub_f32_e32 v240, v240, v222
	v_sub_f32_e32 v241, v241, v222
	v_sub_f32_e32 v242, v242, v222
	v_sub_f32_e32 v243, v243, v222
	v_sub_f32_e32 v244, v244, v222
	v_sub_f32_e32 v245, v245, v222
	v_sub_f32_e32 v246, v246, v222
	v_sub_f32_e32 v247, v247, v222
	v_sub_f32_e32 v248, v248, v222
	v_sub_f32_e32 v249, v249, v222
.LpfU_nr1:
	s_add_i32 s51, s51, 2
	s_add_i32 s53, s53, 0x40000
	s_addk_i32 s52, 0x2000
	s_cmp_lt_i32 s51, s50
	s_cbranch_scc1 .LBB0_822
.Lpe_exit:
	s_waitcnt lgkmcnt(0)
	s_barrier
	v_add_f32_e32 v84, v84, v159
	v_add_f32_e32 v36, v36, v159
	v_add_f32_e32 v85, v85, v159
	v_add_f32_e32 v37, v37, v159
	v_add_f32_e32 v86, v86, v159
	v_add_f32_e32 v38, v38, v159
	v_add_f32_e32 v87, v87, v159
	v_add_f32_e32 v39, v39, v159
	v_add_f32_e32 v88, v88, v159
	v_add_f32_e32 v40, v40, v159
	v_add_f32_e32 v89, v89, v159
	v_add_f32_e32 v41, v41, v159
	v_add_f32_e32 v90, v90, v159
	v_add_f32_e32 v42, v42, v159
	v_add_f32_e32 v91, v91, v159
	v_add_f32_e32 v43, v43, v159
	v_add_f32_e32 v92, v92, v159
	v_add_f32_e32 v44, v44, v159
	v_add_f32_e32 v93, v93, v159
	v_add_f32_e32 v45, v45, v159
	v_add_f32_e32 v94, v94, v159
	v_add_f32_e32 v46, v46, v159
	v_add_f32_e32 v95, v95, v159
	v_add_f32_e32 v47, v47, v159
	v_add_f32_e32 v96, v96, v159
	v_add_f32_e32 v48, v48, v159
	v_add_f32_e32 v97, v97, v159
	v_add_f32_e32 v49, v49, v159
	v_add_f32_e32 v98, v98, v159
	v_add_f32_e32 v50, v50, v159
	v_add_f32_e32 v99, v99, v159
	v_add_f32_e32 v51, v51, v159
	s_branch .LBB0_860
